# attention tile loop: 2-deep K/V global prefetch via two staging register sets chosen by parity, run-ahead prefetch tile state; max3 trees
# baseline (speedup 1.0000x reference)
; #define LAS __attribute__((address_space(3)))
; #define OPQV(x) asm volatile("" : "+v"(x))
; DEV void kv_store(LAS unsigned char* lds, const KVRegs& r, int buf, int tid) {
;     const int key = tid >> 3, c8 = (tid & 7) * 8;
;     unsigned kw = AT_KS + buf * 9216 + (key * 72 + c8) * 2, vw = AT_VT + buf * 9216 + ((tid >> 6) * 8 * 72 + (tid & 63)) * 2; OPQV(kw); OPQV(vw);
;     *(LAS u32x4*)(lds + kw) = r.k;
; #pragma unroll
;     for (int j = 0; j < 4; ++j) { *(LAS bf16_t*)(lds + vw + j * 288) = (bf16_t)(r.v[j] & 0xffffu); *(LAS bf16_t*)(lds + vw + j * 288 + 144) = (bf16_t)(r.v[j] >> 16); }
; }
; DEV void attn_item(LAS unsigned char* lds, const bf16_t* P, const bf16_t* QB, const bf16_t* KV, const bf16_t* KC, const bf16_t* VC, const float* rel_bias, bf16_t* OB, int b, int g, int qt) {
;     ...
;         unsigned rem = anym & (qt >= 31 ? 0xffffffffu : ((2u << qt) - 1u)); rem &= ~1u;
;         int mode = 1, j = 0, buf = 0;
;         for (;;) {
;             kv_store(lds, pre, buf, tid);
;             __syncthreads();
;             int mode_n = mode, j_n = 0; bool more = true;
;             if (mode == 1) { if (rem != 0u) { j_n = __builtin_ctz(rem); rem &= rem - 1u; } else { mode_n = 2; j_n = max(0, qt - 8); } }
;             else { j_n = j + 1; more = j_n <= qt; }
;             if (more) { const bf16_t* base = pbg + (size_t)j_n * 64 * 64 + (mode_n == 1 ? 2 : 4) * KV_TENSOR; pre = kv_fetch(base, base + KV_TENSOR, tid); }
.LBB0_257:
	v_cmp_gt_i32_e32 vcc, s93, v7
	s_and_b64 s[4:5], s[4:5], vcc
	v_cndmask_b32_e64 v7, 0, 1, s[4:5]
	v_cmp_ne_u32_e32 vcc, 0, v7
	s_and_saveexec_b64 s[4:5], s[42:43]
	v_lshl_add_u32 v7, v66, 2, 0
	v_lshrrev_b64 v[60:61], v67, vcc
	v_add_u32_e32 v7, 0x11c00, v7
	v_or_b32_e32 v60, s92, v60
	ds_write_b32 v7, v60
	s_or_b64 exec, exec, s[4:5]
	s_add_i32 s4, 0, 0x11c00
	v_lshl_add_u32 v7, v152, 2, s4
	s_waitcnt lgkmcnt(0)
	s_barrier
	ds_read_b32 v7, v7
	v_lshlrev_b32_e32 v60, 2, v137
	v_lshlrev_b32_e32 v61, 2, v136
	v_add3_u32 v60, s4, v60, v61
	ds_read_b32 v127, v60
	s_waitcnt lgkmcnt(1)
	ds_bpermute_b32 v61, v144, v7
	v_and_b32_e32 v60, 0xffff0000, v149
	v_lshlrev_b32_e32 v126, 16, v149
	s_lshl_b32 s5, 2, s15
	s_waitcnt lgkmcnt(1)
	v_pk_fma_f32 v[134:135], v[126:127], v[2:3], 0 op_sel_hi:[0,1,0]
	s_waitcnt lgkmcnt(0)
	v_or_b32_e32 v7, v61, v7
	v_pk_fma_f32 v[116:117], v[60:61], v[44:45], 0 op_sel_hi:[0,1,0]
	ds_bpermute_b32 v44, v143, v7
	v_xor_b32_e32 v3, 4, v213
	v_pk_fma_f32 v[130:131], v[126:127], v[4:5], 0 op_sel_hi:[0,1,0]
	v_pk_fma_f32 v[132:133], v[126:127], v[32:33], 0 op_sel_hi:[0,1,0]
	s_add_i32 s5, s5, -1
	s_waitcnt lgkmcnt(0)
	v_or_b32_e32 v7, v44, v7
	v_xor_b32_e32 v44, 8, v213
	v_cmp_lt_i32_e32 vcc, v44, v153
	s_and_b32 s5, s5, -2
	s_cmp_lt_u32 s15, 31
	v_cndmask_b32_e32 v44, v213, v44, vcc
	v_lshlrev_b32_e32 v44, 2, v44
	ds_bpermute_b32 v44, v44, v7
	v_cmp_lt_i32_e32 vcc, v3, v153
	s_cselect_b32 s5, s5, -2
	v_pk_fma_f32 v[114:115], v[60:61], v[46:47], 0 op_sel_hi:[0,1,0]
	v_cndmask_b32_e32 v3, v213, v3, vcc
	s_waitcnt lgkmcnt(0)
	v_or_b32_e32 v2, v44, v7
	v_lshlrev_b32_e32 v3, 2, v3
	ds_bpermute_b32 v3, v3, v2
	v_pk_fma_f32 v[110:111], v[60:61], v[50:51], 0 op_sel_hi:[0,1,0]
	v_pk_fma_f32 v[112:113], v[60:61], v[48:49], 0 op_sel_hi:[0,1,0]
	v_pk_fma_f32 v[104:105], v[60:61], v[54:55], 0 op_sel_hi:[0,1,0]
	v_pk_fma_f32 v[108:109], v[60:61], v[52:53], 0 op_sel_hi:[0,1,0]
	s_waitcnt lgkmcnt(0)
	v_or_b32_e32 v4, v3, v2
	v_xor_b32_e32 v2, 2, v213
	v_cmp_lt_i32_e32 vcc, v2, v153
	v_and_b32_e32 v3, 0xffff0000, v148
	v_pk_fma_f32 v[102:103], v[60:61], v[58:59], 0 op_sel_hi:[0,1,0]
	v_cndmask_b32_e32 v2, v213, v2, vcc
	v_lshlrev_b32_e32 v2, 2, v2
	ds_bpermute_b32 v5, v2, v4
	v_lshlrev_b32_e32 v2, 16, v148
	v_mov_b32_e32 v148, 0
	v_pk_fma_f32 v[106:107], v[60:61], v[56:57], 0 op_sel_hi:[0,1,0]
	v_pk_fma_f32 v[128:129], v[126:127], v[34:35], 0 op_sel_hi:[0,1,0]
	s_waitcnt lgkmcnt(0)
	v_or_b32_e32 v32, v5, v4
	v_xor_b32_e32 v4, 1, v213
	v_cmp_lt_i32_e32 vcc, v4, v153
	v_pk_fma_f32 v[120:121], v[126:127], v[38:39], 0 op_sel_hi:[0,1,0]
	v_pk_fma_f32 v[124:125], v[126:127], v[36:37], 0 op_sel_hi:[0,1,0]
	v_cndmask_b32_e32 v4, v213, v4, vcc
	v_lshlrev_b32_e32 v4, 2, v4
	ds_bpermute_b32 v33, v4, v32
	v_pk_fma_f32 v[118:119], v[126:127], v[42:43], 0 op_sel_hi:[0,1,0]
	v_pk_fma_f32 v[122:123], v[126:127], v[40:41], 0 op_sel_hi:[0,1,0]
	v_and_b32_e32 v5, 0xffff0000, v147
	v_lshlrev_b32_e32 v4, 16, v147
	s_waitcnt lgkmcnt(0)
	v_or_b32_e32 v32, v33, v32
	v_add_u32_e32 v33, 0x200, v142
	ds_read2_b32 v[136:137], v33 offset1:129
	v_readfirstlane_b32 s4, v32
	v_mul_lo_u32 v32, v100, s24
	v_or_b32_e32 v32, v32, v152
	v_lshl_add_u32 v146, v32, 1, v221
	v_sub_u32_e64 v32, s15, 8 clamp
	v_mov_b32_e32 v7, v60
	s_mov_b32 s97, 1
	s_and_b32 s95, s4, s5
	v_readfirstlane_b32 s94, v32
	s_sub_i32 s17, 23, s17
	v_add_u32_e32 v145, 0, v145
	s_mov_b32 s50, 0
	v_mov_b32_e32 v150, 0xf149f2ca
	v_mov_b32_e32 v147, 0
	v_mov_b32_e32 v149, 0xf149f2ca
	v_mov_b32_e32 v151, 0
	v_mov_b32_e32 v48, 0
	v_mov_b32_e32 v49, v148
	v_mov_b32_e32 v50, v148
	v_mov_b32_e32 v51, v148
	v_mov_b32_e32 v36, 0
	v_mov_b32_e32 v37, v148
	v_mov_b32_e32 v38, v148
	v_mov_b32_e32 v39, v148
	v_mov_b32_e32 v40, 0
	v_mov_b32_e32 v41, v148
	v_mov_b32_e32 v42, v148
	v_mov_b32_e32 v43, v148
	v_mov_b32_e32 v32, 0
	v_mov_b32_e32 v33, v148
	v_mov_b32_e32 v34, v148
	v_mov_b32_e32 v35, v148
	v_mov_b32_e32 v60, 0
	v_mov_b32_e32 v61, v148
	v_mov_b32_e32 v62, v148
	v_mov_b32_e32 v63, v148
	v_mov_b32_e32 v52, 0
	v_mov_b32_e32 v53, v148
	v_mov_b32_e32 v54, v148
	v_mov_b32_e32 v55, v148
	v_mov_b32_e32 v56, 0
	v_mov_b32_e32 v57, v148
	v_mov_b32_e32 v58, v148
	v_mov_b32_e32 v59, v148
	v_mov_b32_e32 v44, 0
	v_mov_b32_e32 v45, v148
	v_mov_b32_e32 v46, v148
	v_mov_b32_e32 v47, v148
	s_mov_b32 s98, 1
	s_mov_b32 s99, 0
	s_mov_b32 s100, s95
	s_mov_b32 s101, 0
	s_cmp_eq_u32 s98, 1
	s_cbranch_scc0 .Lpf_m2_p
	s_cmp_eq_u32 s100, 0
	s_cbranch_scc1 .Lpf_sw_p
	s_ff1_i32_b32 s99, s100
	s_add_i32 s4, s100, -1
	s_and_b32 s100, s100, s4
	s_branch .Lpf_done_p
.Lpf_sw_p:
	s_mov_b32 s98, 2
	s_mov_b32 s99, s94
	s_branch .Lpf_done_p
.Lpf_m2_p:
	s_add_i32 s99, s99, 1
	s_min_i32 s99, s99, s15
.Lpf_done_p:
	s_lshl_b32 s4, s99, 13
	s_mov_b32 s5, 0x2000000
	s_cmp_eq_u32 s98, 1
	s_cselect_b32 s5, 0x1000000, s5
	s_add_u32 s4, s4, s5
	s_add_u32 s4, s90, s4
	s_addc_u32 s5, s91, 0
	v_lshl_add_u64 v[234:235], s[4:5], 0, v[0:1]
	v_lshl_add_u64 v[234:235], v[100:101], 1, v[234:235]
	v_add_co_u32_e32 v236, vcc, 0x800000, v234
	v_lshl_add_u64 v[232:233], v[98:99], 1, s[4:5]
	s_nop 0
	v_addc_co_u32_e32 v237, vcc, 0, v235, vcc
	global_load_dwordx4 v[232:235], v[232:233], off
	s_nop 0
	global_load_dwordx4 v[236:239], v[236:237], off
.LBB0_260:
	s_movk_i32 s4, 0x2400
	v_mul_lo_u32 v152, v147, s4
	v_add_u32_e32 v64, v152, v139
	v_add_u32_e32 v65, v146, v152
	s_cmp_eq_u32 s101, 0
	s_cbranch_scc0 .Lpf_stB
	s_waitcnt vmcnt(3)
	ds_write_b128 v64, v[24:27]
	v_add_u32_e32 v64, 0, v65
	s_waitcnt vmcnt(2)
	ds_write_b16 v64, v28
	ds_write_b16_d16_hi v64, v28 offset:144
	ds_write_b16 v64, v29 offset:288
	ds_write_b16_d16_hi v64, v29 offset:432
	ds_write_b16 v64, v30 offset:576
	ds_write_b16_d16_hi v64, v30 offset:720
	ds_write_b16 v64, v31 offset:864
	ds_write_b16_d16_hi v64, v31 offset:1008
	s_branch .Lpf_stJ
.Lpf_stB:
	s_waitcnt vmcnt(3)
	ds_write_b128 v64, v[232:235]
	v_add_u32_e32 v64, 0, v65
	s_waitcnt vmcnt(2)
	ds_write_b16 v64, v236
	ds_write_b16_d16_hi v64, v236 offset:144
	ds_write_b16 v64, v237 offset:288
	ds_write_b16_d16_hi v64, v237 offset:432
	ds_write_b16 v64, v238 offset:576
	ds_write_b16_d16_hi v64, v238 offset:720
	ds_write_b16 v64, v239 offset:864
	ds_write_b16_d16_hi v64, v239 offset:1008
.Lpf_stJ:
	s_cmp_eq_u32 s97, 1
	s_cselect_b64 s[46:47], -1, 0
	s_cmp_lg_u32 s97, 1
	s_mov_b64 s[4:5], -1
	s_waitcnt lgkmcnt(0)
	s_barrier
	s_cbranch_scc0 .LBB0_262
	s_add_i32 s52, s50, 1
	s_cmp_lt_i32 s50, s15
	s_mov_b64 s[4:5], 0
	s_cselect_b64 s[54:55], -1, 0

; DEV void attn_item(LAS unsigned char* lds, const bf16_t* P, const bf16_t* QB, const bf16_t* KV, const bf16_t* KC, const bf16_t* VC, const float* rel_bias, bf16_t* OB, int b, int g, int qt) {
;     ...
;             if (mode == 1) { if (rem != 0u) { j_n = __builtin_ctz(rem); rem &= rem - 1u; } else { mode_n = 2; j_n = max(0, qt - 8); } }
;             else { j_n = j + 1; more = j_n <= qt; }
;             if (more) { const bf16_t* base = pbg + (size_t)j_n * 64 * 64 + (mode_n == 1 ? 2 : 4) * KV_TENSOR; pre = kv_fetch(base, base + KV_TENSOR, tid); }
.LBB0_268:
.LBB0_269:
	s_cmp_eq_u32 s98, 1
	s_cbranch_scc0 .Lpf_m2_l
	s_cmp_eq_u32 s100, 0
	s_cbranch_scc1 .Lpf_sw_l
	s_ff1_i32_b32 s99, s100
	s_add_i32 s4, s100, -1
	s_and_b32 s100, s100, s4
	s_branch .Lpf_done_l

; DEV void attn_item(LAS unsigned char* lds, const bf16_t* P, const bf16_t* QB, const bf16_t* KV, const bf16_t* KC, const bf16_t* VC, const float* rel_bias, bf16_t* OB, int b, int g, int qt) {
;     ...
;             if (mode == 1) { if (rem != 0u) { j_n = __builtin_ctz(rem); rem &= rem - 1u; } else { mode_n = 2; j_n = max(0, qt - 8); } }
;             else { j_n = j + 1; more = j_n <= qt; }
;             if (more) { const bf16_t* base = pbg + (size_t)j_n * 64 * 64 + (mode_n == 1 ? 2 : 4) * KV_TENSOR; pre = kv_fetch(base, base + KV_TENSOR, tid); }
.Lpf_done_l:
	s_lshl_b32 s4, s99, 13
	s_mov_b32 s5, 0x2000000
	s_cmp_eq_u32 s98, 1
	s_cselect_b32 s5, 0x1000000, s5
	s_add_u32 s4, s4, s5
	s_add_u32 s4, s90, s4
	s_addc_u32 s5, s91, 0
	s_cmp_eq_u32 s101, 0
	s_cbranch_scc0 .Lpf_ldB
	v_lshl_add_u64 v[26:27], s[4:5], 0, v[0:1]
	v_lshl_add_u64 v[26:27], v[100:101], 1, v[26:27]
	v_add_co_u32_e32 v28, vcc, 0x800000, v26
	v_lshl_add_u64 v[24:25], v[98:99], 1, s[4:5]
	s_nop 0
	v_addc_co_u32_e32 v29, vcc, 0, v27, vcc
	global_load_dwordx4 v[24:27], v[24:25], off
	s_nop 0
	global_load_dwordx4 v[28:31], v[28:29], off
	s_branch .Lpf_ldJ
.Lpf_ldB:
	v_lshl_add_u64 v[234:235], s[4:5], 0, v[0:1]
	v_lshl_add_u64 v[234:235], v[100:101], 1, v[234:235]
	v_add_co_u32_e32 v236, vcc, 0x800000, v234
	v_lshl_add_u64 v[232:233], v[98:99], 1, s[4:5]
	s_nop 0
	v_addc_co_u32_e32 v237, vcc, 0, v235, vcc
	global_load_dwordx4 v[232:235], v[232:233], off
	s_nop 0
	global_load_dwordx4 v[236:239], v[236:237], off

; DEV void attn_item(LAS unsigned char* lds, const bf16_t* P, const bf16_t* QB, const bf16_t* KV, const bf16_t* KC, const bf16_t* VC, const float* rel_bias, bf16_t* OB, int b, int g, int qt) {
;     ...
;             if (mode_n != mode || !more) {
; #pragma unroll
;                 for (int hh = 0; hh < 2; ++hh) { float lt = lrun[hh]; lt += __shfl_xor(lt, 16); lt += __shfl_xor(lt, 32); const float sc = lt > 0.f ? gate[mode][hh] / lt : 0.f;
; #pragma unroll
;                     for (int dt = 0; dt < 4; ++dt) { F[hh][dt] = F[hh][dt] + O[hh][dt] * sc; O[hh][dt] = (f32x4){0.f, 0.f, 0.f, 0.f}; }
;                     mrun[hh] = NEG_; lrun[hh] = 0.f; }
;             }
;             if (!more) break;
;             mode = mode_n; j = j_n; buf ^= 1;
;         }
.LBB0_283:
	v_cndmask_b32_e64 v64, 0, 1, s[54:55]
	v_xor_b32_e32 v147, v147, v64
	s_andn2_b64 vcc, exec, s[92:93]
	s_cbranch_vccz .Lpf_exit
	s_mov_b32 s97, s96
	s_mov_b32 s50, s52
	s_xor_b32 s101, s101, 1
	s_branch .LBB0_260
.Lpf_exit:
	s_waitcnt vmcnt(0)
	s_branch .LBB0_157
